# nt hint also on the rowpass X16/H stores
# baseline (speedup 1.0000x reference)
.LBB0_110:
	s_add_u32 s27, s12, s20
	s_addc_u32 s2, s13, s21
	s_add_i32 s22, s27, 0xffffe000
	s_cmpk_lt_i32 s27, 0x2000
	s_cselect_b32 s3, s2, 0
	s_cselect_b32 s2, s27, s22
	s_cselect_b32 s22, s5, s7
	s_cselect_b32 s23, s4, s6
	s_lshl_b64 s[2:3], s[2:3], 12
	s_add_u32 s2, s23, s2
	s_addc_u32 s3, s22, s3
	global_load_dwordx4 v[44:47], v66, s[2:3] nt
	global_load_dwordx4 v[40:43], v66, s[2:3] offset:1024 nt
	global_load_dwordx4 v[36:39], v66, s[2:3] offset:2048 nt
	global_load_dwordx4 v[32:35], v66, s[2:3] offset:3072 nt
	s_add_i32 s24, s27, 1
	s_add_i32 s22, s27, 0xffffe001
	s_ashr_i32 s25, s24, 31
	s_cmpk_lt_i32 s24, 0x2000
	s_cselect_b32 s3, s25, 0
	s_cselect_b32 s2, s24, s22
	s_cselect_b32 s23, s5, s7
	s_cselect_b32 s22, s4, s6
	s_lshl_b64 s[2:3], s[2:3], 12
	s_add_u32 s22, s22, s2
	s_addc_u32 s23, s23, s3
	s_add_i32 s28, s27, 2
	s_lshl_b64 s[2:3], s[24:25], 11
	s_add_i32 s24, s27, 0xffffe002
	s_ashr_i32 s29, s28, 31
	v_add_co_u32_e32 v56, vcc, s34, v54
	s_cmpk_lt_i32 s28, 0x2000
	s_nop 0
	v_addc_co_u32_e32 v57, vcc, -1, v55, vcc
	v_lshl_add_u64 v[60:61], v[48:49], 0, s[2:3]
	v_lshl_add_u64 v[58:59], v[50:51], 0, s[2:3]
	s_cselect_b32 s3, s29, 0
	s_cselect_b32 s2, s28, s24
	s_cselect_b32 s25, s5, s7
	s_cselect_b32 s24, s4, s6
	s_lshl_b64 s[2:3], s[2:3], 12
	s_add_u32 s24, s24, s2
	s_addc_u32 s25, s25, s3
	s_add_i32 s26, s27, 3
	s_lshl_b64 s[2:3], s[28:29], 11
	s_add_i32 s28, s27, 0xffffe003
	s_ashr_i32 s27, s26, 31
	s_cmpk_lt_i32 s26, 0x2000
	v_lshl_add_u64 v[64:65], v[48:49], 0, s[2:3]
	v_lshl_add_u64 v[62:63], v[50:51], 0, s[2:3]
	s_cselect_b32 s3, s27, 0
	s_cselect_b32 s2, s26, s28
	s_cselect_b32 s29, s5, s7
	s_cselect_b32 s28, s4, s6
	s_lshl_b64 s[2:3], s[2:3], 12
	s_add_u32 s28, s28, s2
	s_addc_u32 s29, s29, s3
	s_waitcnt vmcnt(3)
	v_cvt_pk_bf16_f32 v72, v44, v45
	v_mul_f32_e32 v74, v45, v45
	v_mul_f32_e32 v75, v47, v47
	s_waitcnt vmcnt(2)
	v_mul_f32_e32 v76, v41, v41
	v_mul_f32_e32 v77, v43, v43
	v_cvt_pk_bf16_f32 v73, v46, v47
	s_waitcnt vmcnt(1)
	v_mul_f32_e32 v78, v37, v37
	v_mul_f32_e32 v79, v39, v39
	global_store_dwordx2 v[54:55], v[72:73], off offset:-1536 nt
	v_cvt_pk_bf16_f32 v72, v40, v41
	v_fmac_f32_e32 v74, v44, v44
	v_fmac_f32_e32 v75, v46, v46
	v_fmac_f32_e32 v76, v40, v40
	v_fmac_f32_e32 v77, v42, v42
	s_waitcnt vmcnt(1)
	v_mul_f32_e32 v80, v33, v33
	v_mul_f32_e32 v81, v35, v35
	v_cvt_pk_bf16_f32 v73, v42, v43
	v_fmac_f32_e32 v78, v36, v36
	v_fmac_f32_e32 v79, v38, v38
	global_store_dwordx2 v[54:55], v[72:73], off offset:-1024 nt
	v_cvt_pk_bf16_f32 v72, v36, v37
	v_add_f32_e32 v74, v74, v75
	v_add_f32_e32 v75, v76, v77
	v_fmac_f32_e32 v80, v32, v32
	v_fmac_f32_e32 v81, v34, v34
	v_cvt_pk_bf16_f32 v73, v38, v39
	v_add_f32_e32 v76, v78, v79
	global_store_dwordx2 v[54:55], v[72:73], off offset:-512 nt
	v_cvt_pk_bf16_f32 v72, v32, v33
	v_add_f32_e32 v74, v74, v75
	v_add_f32_e32 v77, v80, v81
	v_cvt_pk_bf16_f32 v73, v34, v35
	global_store_dwordx2 v[54:55], v[72:73], off nt
	v_add_f32_e32 v72, v74, v76
	v_add_f32_e32 v72, v72, v77
	v_lshl_add_u64 v[54:55], v[54:55], 0, s[18:19]
	s_nop 0
	v_add_f32_dpp v72, v72, v72 row_ror:8 row_mask:0xf bank_mask:0xf bound_ctrl:1
	s_nop 1
	v_add_f32_dpp v72, v72, v72 row_ror:4 row_mask:0xf bank_mask:0xf bound_ctrl:1
	s_nop 1
	v_add_f32_dpp v72, v72, v72 row_ror:2 row_mask:0xf bank_mask:0xf bound_ctrl:1
	s_nop 1
	v_add_f32_dpp v72, v72, v72 row_ror:1 row_mask:0xf bank_mask:0xf bound_ctrl:1
	v_mov_b32_e32 v73, v72
	s_nop 1
	v_permlane16_swap_b32_e32 v72, v73
	v_add_f32_e32 v72, v72, v73
	v_mov_b32_e32 v73, v72
	s_nop 1
	v_permlane32_swap_b32_e32 v72, v73
	v_add_f32_e32 v72, v72, v73
	v_fmamk_f32 v72, v72, 0x3a800000, v70
	v_mul_f32_e32 v73, 0x4f800000, v72
	v_cmp_gt_f32_e32 vcc, s33, v72
	s_nop 1
	v_cndmask_b32_e32 v72, v72, v73, vcc
	v_sqrt_f32_e32 v73, v72
	s_nop 0
	v_add_u32_e32 v74, -1, v73
	v_add_u32_e32 v75, 1, v73
	v_fma_f32 v76, -v74, v73, v72
	v_fma_f32 v77, -v75, v73, v72
	v_cmp_ge_f32_e64 s[2:3], 0, v76
	s_nop 1
	v_cndmask_b32_e64 v73, v73, v74, s[2:3]
	v_cmp_lt_f32_e64 s[2:3], 0, v77
	s_nop 1
	v_cndmask_b32_e64 v73, v73, v75, s[2:3]
	v_mul_f32_e32 v74, 0x37800000, v73
	v_cndmask_b32_e32 v73, v73, v74, vcc
	v_cmp_class_f32_e32 vcc, v72, v71
	s_nop 1
	v_cndmask_b32_e32 v72, v73, v72, vcc
	v_div_scale_f32 v73, s[2:3], v72, v72, 1.0
	v_rcp_f32_e32 v75, v73
	v_div_scale_f32 v74, vcc, 1.0, v72, 1.0
	v_fma_f32 v76, -v73, v75, 1.0
	v_fmac_f32_e32 v75, v76, v75
	v_mul_f32_e32 v76, v74, v75
	v_fma_f32 v77, -v73, v76, v74
	v_fmac_f32_e32 v76, v77, v75
	v_fma_f32 v73, -v73, v76, v74
	v_div_fmas_f32 v73, v73, v75, v76
	v_div_fixup_f32 v72, v73, v72, 1.0
	v_pk_mul_f32 v[44:45], v[44:45], v[72:73] op_sel_hi:[1,0]
	v_pk_mul_f32 v[40:41], v[40:41], v[72:73] op_sel_hi:[1,0]
	v_pk_mul_f32 v[36:37], v[36:37], v[72:73] op_sel_hi:[1,0]
	v_pk_mul_f32 v[32:33], v[32:33], v[72:73] op_sel_hi:[1,0]
	v_pk_mul_f32 v[46:47], v[46:47], v[72:73] op_sel_hi:[1,0]
	v_pk_mul_f32 v[42:43], v[42:43], v[72:73] op_sel_hi:[1,0]
	v_pk_mul_f32 v[38:39], v[38:39], v[72:73] op_sel_hi:[1,0]
	v_pk_mul_f32 v[34:35], v[34:35], v[72:73] op_sel_hi:[1,0]
	v_pk_fma_f32 v[44:45], v[8:9], v[44:45], v[0:1]
	v_pk_fma_f32 v[40:41], v[12:13], v[40:41], v[4:5]
	v_pk_fma_f32 v[36:37], v[24:25], v[36:37], v[16:17]
	v_pk_fma_f32 v[32:33], v[28:29], v[32:33], v[20:21]
	v_pk_fma_f32 v[46:47], v[10:11], v[46:47], v[2:3]
	v_pk_fma_f32 v[42:43], v[14:15], v[42:43], v[6:7]
	v_pk_fma_f32 v[38:39], v[26:27], v[38:39], v[18:19]
	v_pk_fma_f32 v[34:35], v[30:31], v[34:35], v[22:23]
	v_cvt_pk_bf16_f32 v44, v44, v45
	v_cvt_pk_bf16_f32 v45, v46, v47
	global_store_dwordx2 v[56:57], v[44:45], off offset:-1536 nt
	v_cvt_pk_bf16_f32 v40, v40, v41
	v_cvt_pk_bf16_f32 v41, v42, v43
	global_store_dwordx2 v[56:57], v[40:41], off offset:-1024 nt
	v_cvt_pk_bf16_f32 v36, v36, v37
	v_cvt_pk_bf16_f32 v37, v38, v39
	global_store_dwordx2 v[56:57], v[36:37], off offset:-512 nt
	v_cvt_pk_bf16_f32 v32, v32, v33
	v_cvt_pk_bf16_f32 v33, v34, v35
	global_store_dwordx2 v[56:57], v[32:33], off nt
	global_load_dwordx4 v[32:35], v66, s[22:23] nt
	s_nop 0
	global_load_dwordx4 v[36:39], v66, s[22:23] offset:1024 nt
	global_load_dwordx4 v[40:43], v66, s[22:23] offset:2048 nt
	global_load_dwordx4 v[44:47], v66, s[22:23] offset:3072 nt
	s_waitcnt vmcnt(3)
	v_cvt_pk_bf16_f32 v56, v32, v33
	v_mul_f32_e32 v72, v33, v33
	v_mul_f32_e32 v73, v35, v35
	s_waitcnt vmcnt(2)
	v_mul_f32_e32 v74, v37, v37
	v_mul_f32_e32 v75, v39, v39
	v_cvt_pk_bf16_f32 v57, v34, v35
	s_waitcnt vmcnt(1)
	v_mul_f32_e32 v76, v41, v41
	v_mul_f32_e32 v77, v43, v43
	global_store_dwordx2 v[60:61], v[56:57], off nt
	v_cvt_pk_bf16_f32 v56, v36, v37
	v_fmac_f32_e32 v72, v32, v32
	v_fmac_f32_e32 v73, v34, v34
	v_fmac_f32_e32 v74, v36, v36
	v_fmac_f32_e32 v75, v38, v38
	s_waitcnt vmcnt(1)
	v_mul_f32_e32 v78, v45, v45
	v_mul_f32_e32 v79, v47, v47
	v_cvt_pk_bf16_f32 v57, v38, v39
	v_fmac_f32_e32 v76, v40, v40
	v_fmac_f32_e32 v77, v42, v42
	global_store_dwordx2 v[60:61], v[56:57], off offset:512 nt
	v_cvt_pk_bf16_f32 v56, v40, v41
	v_add_f32_e32 v72, v72, v73
	v_add_f32_e32 v73, v74, v75
	v_fmac_f32_e32 v78, v44, v44
	v_fmac_f32_e32 v79, v46, v46
	v_cvt_pk_bf16_f32 v57, v42, v43
	v_add_f32_e32 v74, v76, v77
	global_store_dwordx2 v[60:61], v[56:57], off offset:1024 nt
	v_cvt_pk_bf16_f32 v56, v44, v45
	v_add_f32_e32 v72, v72, v73
	v_add_f32_e32 v75, v78, v79
	v_cvt_pk_bf16_f32 v57, v46, v47
	global_store_dwordx2 v[60:61], v[56:57], off offset:1536 nt
	v_add_f32_e32 v56, v72, v74
	v_add_f32_e32 v56, v56, v75
	s_nop 1
	v_add_f32_dpp v56, v56, v56 row_ror:8 row_mask:0xf bank_mask:0xf bound_ctrl:1
	s_nop 1
	v_add_f32_dpp v56, v56, v56 row_ror:4 row_mask:0xf bank_mask:0xf bound_ctrl:1
	s_nop 1
	v_add_f32_dpp v56, v56, v56 row_ror:2 row_mask:0xf bank_mask:0xf bound_ctrl:1
	s_nop 1
	v_add_f32_dpp v56, v56, v56 row_ror:1 row_mask:0xf bank_mask:0xf bound_ctrl:1
	v_mov_b32_e32 v57, v56
	s_nop 1
	v_permlane16_swap_b32_e32 v56, v57
	v_add_f32_e32 v56, v56, v57
	v_mov_b32_e32 v57, v56
	s_nop 1
	v_permlane32_swap_b32_e32 v56, v57
	v_add_f32_e32 v56, v56, v57
	v_fmamk_f32 v56, v56, 0x3a800000, v70
	v_mul_f32_e32 v57, 0x4f800000, v56
	v_cmp_gt_f32_e32 vcc, s33, v56
	s_nop 1
	v_cndmask_b32_e32 v56, v56, v57, vcc
	v_sqrt_f32_e32 v57, v56
	s_nop 0
	v_add_u32_e32 v60, -1, v57
	v_add_u32_e32 v61, 1, v57
	v_fma_f32 v72, -v60, v57, v56
	v_fma_f32 v73, -v61, v57, v56
	v_cmp_ge_f32_e64 s[2:3], 0, v72
	s_nop 1
	v_cndmask_b32_e64 v57, v57, v60, s[2:3]
	v_cmp_lt_f32_e64 s[2:3], 0, v73
	s_nop 1
	v_cndmask_b32_e64 v57, v57, v61, s[2:3]
	v_mul_f32_e32 v60, 0x37800000, v57
	v_cndmask_b32_e32 v57, v57, v60, vcc
	v_cmp_class_f32_e32 vcc, v56, v71
	s_nop 1
	v_cndmask_b32_e32 v56, v57, v56, vcc
	v_div_scale_f32 v57, s[2:3], v56, v56, 1.0
	v_rcp_f32_e32 v61, v57
	v_div_scale_f32 v60, vcc, 1.0, v56, 1.0
	v_fma_f32 v72, -v57, v61, 1.0
	v_fmac_f32_e32 v61, v72, v61
	v_mul_f32_e32 v72, v60, v61
	v_fma_f32 v73, -v57, v72, v60
	v_fmac_f32_e32 v72, v73, v61
	v_fma_f32 v57, -v57, v72, v60
	v_div_fmas_f32 v57, v57, v61, v72
	v_div_fixup_f32 v56, v57, v56, 1.0
	v_pk_mul_f32 v[32:33], v[32:33], v[56:57] op_sel_hi:[1,0]
	v_pk_mul_f32 v[34:35], v[34:35], v[56:57] op_sel_hi:[1,0]
	v_pk_fma_f32 v[32:33], v[8:9], v[32:33], v[0:1]
	v_pk_mul_f32 v[36:37], v[36:37], v[56:57] op_sel_hi:[1,0]
	v_pk_mul_f32 v[38:39], v[38:39], v[56:57] op_sel_hi:[1,0]
	v_pk_fma_f32 v[34:35], v[10:11], v[34:35], v[2:3]
	v_cvt_pk_bf16_f32 v32, v32, v33
	v_pk_mul_f32 v[40:41], v[40:41], v[56:57] op_sel_hi:[1,0]
	v_cvt_pk_bf16_f32 v33, v34, v35
	v_pk_mul_f32 v[42:43], v[42:43], v[56:57] op_sel_hi:[1,0]
	v_pk_fma_f32 v[38:39], v[14:15], v[38:39], v[6:7]
	v_pk_fma_f32 v[36:37], v[12:13], v[36:37], v[4:5]
	global_store_dwordx2 v[58:59], v[32:33], off nt
	v_cvt_pk_bf16_f32 v32, v36, v37
	v_cvt_pk_bf16_f32 v33, v38, v39
	v_pk_mul_f32 v[44:45], v[44:45], v[56:57] op_sel_hi:[1,0]
	v_pk_mul_f32 v[46:47], v[46:47], v[56:57] op_sel_hi:[1,0]
	v_pk_fma_f32 v[42:43], v[26:27], v[42:43], v[18:19]
	v_pk_fma_f32 v[40:41], v[24:25], v[40:41], v[16:17]
	global_store_dwordx2 v[58:59], v[32:33], off offset:512 nt
	v_cvt_pk_bf16_f32 v32, v40, v41
	v_cvt_pk_bf16_f32 v33, v42, v43
	v_pk_fma_f32 v[46:47], v[30:31], v[46:47], v[22:23]
	v_pk_fma_f32 v[44:45], v[28:29], v[44:45], v[20:21]
	global_store_dwordx2 v[58:59], v[32:33], off offset:1024 nt
	v_cvt_pk_bf16_f32 v32, v44, v45
	v_cvt_pk_bf16_f32 v33, v46, v47
	global_store_dwordx2 v[58:59], v[32:33], off offset:1536 nt
	global_load_dwordx4 v[32:35], v66, s[24:25] nt
	s_nop 0
	global_load_dwordx4 v[36:39], v66, s[24:25] offset:1024 nt
	global_load_dwordx4 v[40:43], v66, s[24:25] offset:2048 nt
	global_load_dwordx4 v[44:47], v66, s[24:25] offset:3072 nt
	s_waitcnt vmcnt(3)
	v_cvt_pk_bf16_f32 v56, v32, v33
	v_mul_f32_e32 v58, v33, v33
	v_mul_f32_e32 v59, v35, v35
	s_waitcnt vmcnt(2)
	v_mul_f32_e32 v60, v37, v37
	v_mul_f32_e32 v61, v39, v39
	v_cvt_pk_bf16_f32 v57, v34, v35
	s_waitcnt vmcnt(1)
	v_mul_f32_e32 v72, v41, v41
	v_mul_f32_e32 v73, v43, v43
	global_store_dwordx2 v[64:65], v[56:57], off nt
	v_cvt_pk_bf16_f32 v56, v36, v37
	v_fmac_f32_e32 v58, v32, v32
	v_fmac_f32_e32 v59, v34, v34
	v_fmac_f32_e32 v60, v36, v36
	v_fmac_f32_e32 v61, v38, v38
	s_waitcnt vmcnt(1)
	v_mul_f32_e32 v74, v45, v45
	v_mul_f32_e32 v75, v47, v47
	v_cvt_pk_bf16_f32 v57, v38, v39
	v_fmac_f32_e32 v72, v40, v40
	v_fmac_f32_e32 v73, v42, v42
	global_store_dwordx2 v[64:65], v[56:57], off offset:512 nt
	v_cvt_pk_bf16_f32 v56, v40, v41
	v_add_f32_e32 v58, v58, v59
	v_add_f32_e32 v59, v60, v61
	v_fmac_f32_e32 v74, v44, v44
	v_fmac_f32_e32 v75, v46, v46
	v_cvt_pk_bf16_f32 v57, v42, v43
	v_add_f32_e32 v60, v72, v73
	global_store_dwordx2 v[64:65], v[56:57], off offset:1024 nt
	v_cvt_pk_bf16_f32 v56, v44, v45
	v_add_f32_e32 v58, v58, v59
	v_add_f32_e32 v61, v74, v75
	v_cvt_pk_bf16_f32 v57, v46, v47
	global_store_dwordx2 v[64:65], v[56:57], off offset:1536 nt
	v_add_f32_e32 v56, v58, v60
	v_add_f32_e32 v56, v56, v61
	s_nop 1
	v_add_f32_dpp v56, v56, v56 row_ror:8 row_mask:0xf bank_mask:0xf bound_ctrl:1
	s_nop 1
	v_add_f32_dpp v56, v56, v56 row_ror:4 row_mask:0xf bank_mask:0xf bound_ctrl:1
	s_nop 1
	v_add_f32_dpp v56, v56, v56 row_ror:2 row_mask:0xf bank_mask:0xf bound_ctrl:1
	s_nop 1
	v_add_f32_dpp v56, v56, v56 row_ror:1 row_mask:0xf bank_mask:0xf bound_ctrl:1
	v_mov_b32_e32 v57, v56
	s_nop 1
	v_permlane16_swap_b32_e32 v56, v57
	v_add_f32_e32 v56, v56, v57
	v_mov_b32_e32 v57, v56
	s_nop 1
	v_permlane32_swap_b32_e32 v56, v57
	v_add_f32_e32 v56, v56, v57
	v_fmamk_f32 v56, v56, 0x3a800000, v70
	v_mul_f32_e32 v57, 0x4f800000, v56
	v_cmp_gt_f32_e32 vcc, s33, v56
	s_nop 1
	v_cndmask_b32_e32 v56, v56, v57, vcc
	v_sqrt_f32_e32 v57, v56
	s_nop 0
	v_add_u32_e32 v58, -1, v57
	v_add_u32_e32 v59, 1, v57
	v_fma_f32 v60, -v58, v57, v56
	v_fma_f32 v61, -v59, v57, v56
	v_cmp_ge_f32_e64 s[2:3], 0, v60
	s_nop 1
	v_cndmask_b32_e64 v57, v57, v58, s[2:3]
	v_cmp_lt_f32_e64 s[2:3], 0, v61
	s_nop 1
	v_cndmask_b32_e64 v57, v57, v59, s[2:3]
	v_mul_f32_e32 v58, 0x37800000, v57
	v_cndmask_b32_e32 v57, v57, v58, vcc
	v_cmp_class_f32_e32 vcc, v56, v71
	s_nop 1
	v_cndmask_b32_e32 v56, v57, v56, vcc
	v_div_scale_f32 v57, s[2:3], v56, v56, 1.0
	v_rcp_f32_e32 v59, v57
	v_div_scale_f32 v58, vcc, 1.0, v56, 1.0
	s_lshl_b64 s[2:3], s[26:27], 11
	v_fma_f32 v60, -v57, v59, 1.0
	v_fmac_f32_e32 v59, v60, v59
	v_mul_f32_e32 v60, v58, v59
	v_fma_f32 v61, -v57, v60, v58
	v_fmac_f32_e32 v60, v61, v59
	v_fma_f32 v57, -v57, v60, v58
	v_div_fmas_f32 v57, v57, v59, v60
	v_div_fixup_f32 v56, v57, v56, 1.0
	v_pk_mul_f32 v[32:33], v[32:33], v[56:57] op_sel_hi:[1,0]
	v_pk_mul_f32 v[34:35], v[34:35], v[56:57] op_sel_hi:[1,0]
	v_pk_fma_f32 v[32:33], v[8:9], v[32:33], v[0:1]
	v_pk_mul_f32 v[36:37], v[36:37], v[56:57] op_sel_hi:[1,0]
	v_pk_mul_f32 v[38:39], v[38:39], v[56:57] op_sel_hi:[1,0]
	v_pk_fma_f32 v[34:35], v[10:11], v[34:35], v[2:3]
	v_cvt_pk_bf16_f32 v32, v32, v33
	v_pk_mul_f32 v[40:41], v[40:41], v[56:57] op_sel_hi:[1,0]
	v_cvt_pk_bf16_f32 v33, v34, v35
	v_pk_mul_f32 v[42:43], v[42:43], v[56:57] op_sel_hi:[1,0]
	v_pk_fma_f32 v[38:39], v[14:15], v[38:39], v[6:7]
	v_pk_fma_f32 v[36:37], v[12:13], v[36:37], v[4:5]
	global_store_dwordx2 v[62:63], v[32:33], off nt
	v_cvt_pk_bf16_f32 v32, v36, v37
	v_cvt_pk_bf16_f32 v33, v38, v39
	v_pk_mul_f32 v[44:45], v[44:45], v[56:57] op_sel_hi:[1,0]
	v_pk_mul_f32 v[46:47], v[46:47], v[56:57] op_sel_hi:[1,0]
	v_pk_fma_f32 v[42:43], v[26:27], v[42:43], v[18:19]
	v_pk_fma_f32 v[40:41], v[24:25], v[40:41], v[16:17]
	global_store_dwordx2 v[62:63], v[32:33], off offset:512 nt
	v_cvt_pk_bf16_f32 v32, v40, v41
	v_cvt_pk_bf16_f32 v33, v42, v43
	v_pk_fma_f32 v[46:47], v[30:31], v[46:47], v[22:23]
	v_pk_fma_f32 v[44:45], v[28:29], v[44:45], v[20:21]
	global_store_dwordx2 v[62:63], v[32:33], off offset:1024 nt
	v_cvt_pk_bf16_f32 v32, v44, v45
	v_cvt_pk_bf16_f32 v33, v46, v47
	global_store_dwordx2 v[62:63], v[32:33], off offset:1536 nt
	global_load_dwordx4 v[32:35], v66, s[28:29] nt
	s_nop 0
	global_load_dwordx4 v[36:39], v66, s[28:29] offset:1024 nt
	global_load_dwordx4 v[40:43], v66, s[28:29] offset:2048 nt
	global_load_dwordx4 v[44:47], v66, s[28:29] offset:3072 nt
	v_lshl_add_u64 v[56:57], v[48:49], 0, s[2:3]
	s_waitcnt vmcnt(3)
	v_cvt_pk_bf16_f32 v60, v32, v33
	v_mul_f32_e32 v62, v33, v33
	v_mul_f32_e32 v63, v35, v35
	s_waitcnt vmcnt(2)
	v_mul_f32_e32 v64, v37, v37
	v_mul_f32_e32 v65, v39, v39
	v_cvt_pk_bf16_f32 v61, v34, v35
	s_waitcnt vmcnt(1)
	v_mul_f32_e32 v72, v41, v41
	v_mul_f32_e32 v73, v43, v43
	v_fmac_f32_e32 v62, v32, v32
	v_fmac_f32_e32 v63, v34, v34
	v_fmac_f32_e32 v64, v36, v36
	v_fmac_f32_e32 v65, v38, v38
	s_waitcnt vmcnt(0)
	v_mul_f32_e32 v74, v45, v45
	v_mul_f32_e32 v75, v47, v47
	global_store_dwordx2 v[56:57], v[60:61], off nt
	v_cvt_pk_bf16_f32 v60, v36, v37
	v_cvt_pk_bf16_f32 v61, v38, v39
	v_fmac_f32_e32 v72, v40, v40
	v_fmac_f32_e32 v73, v42, v42
	v_add_f32_e32 v62, v62, v63
	v_add_f32_e32 v63, v64, v65
	v_fmac_f32_e32 v74, v44, v44
	v_fmac_f32_e32 v75, v46, v46
	global_store_dwordx2 v[56:57], v[60:61], off offset:512 nt
	v_cvt_pk_bf16_f32 v60, v40, v41
	v_cvt_pk_bf16_f32 v61, v42, v43
	v_add_f32_e32 v64, v72, v73
	v_add_f32_e32 v62, v62, v63
	v_add_f32_e32 v65, v74, v75
	global_store_dwordx2 v[56:57], v[60:61], off offset:1024 nt
	v_cvt_pk_bf16_f32 v60, v44, v45
	v_cvt_pk_bf16_f32 v61, v46, v47
	global_store_dwordx2 v[56:57], v[60:61], off offset:1536 nt
	v_add_f32_e32 v56, v62, v64
	v_add_f32_e32 v56, v56, v65
	v_lshl_add_u64 v[58:59], v[50:51], 0, s[2:3]
	s_add_u32 s20, s20, 4
	v_add_f32_dpp v56, v56, v56 row_ror:8 row_mask:0xf bank_mask:0xf bound_ctrl:1
	s_addc_u32 s21, s21, 0
	s_cmp_eq_u32 s20, 8
	v_add_f32_dpp v56, v56, v56 row_ror:4 row_mask:0xf bank_mask:0xf bound_ctrl:1
	s_nop 1
	v_add_f32_dpp v56, v56, v56 row_ror:2 row_mask:0xf bank_mask:0xf bound_ctrl:1
	s_nop 1
	v_add_f32_dpp v56, v56, v56 row_ror:1 row_mask:0xf bank_mask:0xf bound_ctrl:1
	v_mov_b32_e32 v57, v56
	s_nop 1
	v_permlane16_swap_b32_e32 v56, v57
	v_add_f32_e32 v56, v56, v57
	v_mov_b32_e32 v57, v56
	s_nop 1
	v_permlane32_swap_b32_e32 v56, v57
	v_add_f32_e32 v56, v56, v57
	v_fmamk_f32 v56, v56, 0x3a800000, v70
	v_mul_f32_e32 v57, 0x4f800000, v56
	v_cmp_gt_f32_e32 vcc, s33, v56
	s_nop 1
	v_cndmask_b32_e32 v56, v56, v57, vcc
	v_sqrt_f32_e32 v57, v56
	s_nop 0
	v_add_u32_e32 v60, -1, v57
	v_add_u32_e32 v61, 1, v57
	v_fma_f32 v62, -v60, v57, v56
	v_fma_f32 v63, -v61, v57, v56
	v_cmp_ge_f32_e64 s[2:3], 0, v62
	s_nop 1
	v_cndmask_b32_e64 v57, v57, v60, s[2:3]
	v_cmp_lt_f32_e64 s[2:3], 0, v63
	s_nop 1
	v_cndmask_b32_e64 v57, v57, v61, s[2:3]
	v_mul_f32_e32 v60, 0x37800000, v57
	v_cndmask_b32_e32 v57, v57, v60, vcc
	v_cmp_class_f32_e32 vcc, v56, v71
	s_nop 1
	v_cndmask_b32_e32 v56, v57, v56, vcc
	v_div_scale_f32 v57, s[2:3], v56, v56, 1.0
	v_rcp_f32_e32 v61, v57
	v_div_scale_f32 v60, vcc, 1.0, v56, 1.0
	v_fma_f32 v62, -v57, v61, 1.0
	v_fmac_f32_e32 v61, v62, v61
	v_mul_f32_e32 v62, v60, v61
	v_fma_f32 v63, -v57, v62, v60
	v_fmac_f32_e32 v62, v63, v61
	v_fma_f32 v57, -v57, v62, v60
	v_div_fmas_f32 v57, v57, v61, v62
	v_div_fixup_f32 v56, v57, v56, 1.0
	v_pk_mul_f32 v[32:33], v[32:33], v[56:57] op_sel_hi:[1,0]
	v_pk_mul_f32 v[34:35], v[34:35], v[56:57] op_sel_hi:[1,0]
	v_pk_fma_f32 v[32:33], v[8:9], v[32:33], v[0:1]
	v_pk_mul_f32 v[36:37], v[36:37], v[56:57] op_sel_hi:[1,0]
	v_pk_mul_f32 v[38:39], v[38:39], v[56:57] op_sel_hi:[1,0]
	v_pk_fma_f32 v[34:35], v[10:11], v[34:35], v[2:3]
	v_cvt_pk_bf16_f32 v32, v32, v33
	v_pk_mul_f32 v[40:41], v[40:41], v[56:57] op_sel_hi:[1,0]
	v_cvt_pk_bf16_f32 v33, v34, v35
	v_pk_mul_f32 v[42:43], v[42:43], v[56:57] op_sel_hi:[1,0]
	v_pk_fma_f32 v[38:39], v[14:15], v[38:39], v[6:7]
	v_pk_fma_f32 v[36:37], v[12:13], v[36:37], v[4:5]
	global_store_dwordx2 v[58:59], v[32:33], off nt
	v_cvt_pk_bf16_f32 v32, v36, v37
	v_cvt_pk_bf16_f32 v33, v38, v39
	v_pk_mul_f32 v[44:45], v[44:45], v[56:57] op_sel_hi:[1,0]
	v_pk_mul_f32 v[46:47], v[46:47], v[56:57] op_sel_hi:[1,0]
	v_pk_fma_f32 v[42:43], v[26:27], v[42:43], v[18:19]
	v_pk_fma_f32 v[40:41], v[24:25], v[40:41], v[16:17]
	global_store_dwordx2 v[58:59], v[32:33], off offset:512 nt
	v_cvt_pk_bf16_f32 v32, v40, v41
	v_cvt_pk_bf16_f32 v33, v42, v43
	v_pk_fma_f32 v[46:47], v[30:31], v[46:47], v[22:23]
	v_pk_fma_f32 v[44:45], v[28:29], v[44:45], v[20:21]
	global_store_dwordx2 v[58:59], v[32:33], off offset:1024 nt
	v_cvt_pk_bf16_f32 v32, v44, v45
	v_cvt_pk_bf16_f32 v33, v46, v47
	global_store_dwordx2 v[58:59], v[32:33], off offset:1536 nt
	s_cbranch_scc0 .LBB0_110
	s_add_u32 s12, s12, s14
	s_addc_u32 s13, s13, s15
	s_cmpk_gt_i32 s12, 0x3fff
	v_lshl_add_u64 v[52:53], v[52:53], 0, s[16:17]
	s_cbranch_scc0 .LBB0_109
